# re-measure: nt cache hints + interleaved dequant scales
# speedup vs baseline: 1.0093x; 1.0051x over previous
; __device__ __forceinline__ unsigned xb_ld(unsigned* p)              { return __hip_atomic_load(p, __ATOMIC_RELAXED, __HIP_MEMORY_SCOPE_AGENT); }
; __device__ __forceinline__ unsigned xb_add(unsigned* p, unsigned v) { return __hip_atomic_fetch_add(p, v, __ATOMIC_RELAXED, __HIP_MEMORY_SCOPE_AGENT); }
; #define XB_SPIN(cond, bar) do { unsigned _sp = 0; while (cond) { __builtin_amdgcn_s_sleep(4); \
;     if ((++_sp & 255u) == 0u) { if (xb_ld(&(bar)[XB_TMO])) break; if (_sp > XB_SPIN_CAP) { atomicAdd(&(bar)[XB_TMO], 1u); break; } } } } while (0)
; __device__ __forceinline__ void xcd_barrier_conv(const XcdBarrier& b, int k, bool conv, const float* U, const float* V, unsigned char* ws, LAS unsigned char* lds) {
;     ...
;             else XB_SPIN(xb_ld(&bar[XB_TOPGEN]) == tg, bar);
;             __builtin_amdgcn_fence(__ATOMIC_ACQUIRE, "agent");
;             xb_add(&bar[XB_XGEN(b.x)], 1u);
;             asm volatile("s_waitcnt vmcnt(0)" ::: "memory");
;         } else {
;             XB_SPIN(xb_ld(&bar[XB_XGEN(b.x)]) == gen, bar);
.LBB0_109:
	s_and_b32 s20, s24, 0xff
	s_mov_b64 s[18:19], -1
	s_cmp_lg_u32 s20, 0
	s_mov_b64 s[22:23], -1
	s_sleep 8
	s_cbranch_scc1 .LBB0_112
	global_load_dword v3, v1, s[12:13] sc1
	s_waitcnt vmcnt(0)
	v_cmp_eq_u32_e32 vcc, 0, v3
	s_cbranch_vccnz .LBB0_114
	s_mov_b64 s[22:23], 0
	s_mov_b64 s[20:21], -1

; __device__ __forceinline__ unsigned xb_ld(unsigned* p)              { return __hip_atomic_load(p, __ATOMIC_RELAXED, __HIP_MEMORY_SCOPE_AGENT); }
; __device__ __forceinline__ unsigned xb_add(unsigned* p, unsigned v) { return __hip_atomic_fetch_add(p, v, __ATOMIC_RELAXED, __HIP_MEMORY_SCOPE_AGENT); }
; #define XB_SPIN(cond, bar) do { unsigned _sp = 0; while (cond) { __builtin_amdgcn_s_sleep(4); \
;     if ((++_sp & 255u) == 0u) { if (xb_ld(&(bar)[XB_TMO])) break; if (_sp > XB_SPIN_CAP) { atomicAdd(&(bar)[XB_TMO], 1u); break; } } } } while (0)
; __device__ __forceinline__ void xcd_barrier_conv(const XcdBarrier& b, int k, bool conv, const float* U, const float* V, unsigned char* ws, LAS unsigned char* lds) {
;     ...
;             else XB_SPIN(xb_ld(&bar[XB_TOPGEN]) == tg, bar);
;             __builtin_amdgcn_fence(__ATOMIC_ACQUIRE, "agent");
;             xb_add(&bar[XB_XGEN(b.x)], 1u);
;             asm volatile("s_waitcnt vmcnt(0)" ::: "memory");
;         } else {
;             XB_SPIN(xb_ld(&bar[XB_XGEN(b.x)]) == gen, bar);
.LBB0_126:
	s_and_b32 s18, s24, 0xff
	s_cmp_lg_u32 s18, 0
	s_mov_b64 s[20:21], -1
	s_sleep 8
	s_cbranch_scc1 .LBB0_129
	global_load_dword v2, v1, s[12:13] sc1
	s_waitcnt vmcnt(0)
	v_cmp_eq_u32_e32 vcc, 0, v2
	s_cbranch_vccnz .LBB0_131
	s_mov_b64 s[20:21], 0
	s_mov_b64 s[18:19], -1
